# up-projection GEMM: the 96 tiles of the last round are split along K between workgroup c and the idle workgroup c+96; partial accumulators exchanged through workspace
# baseline (speedup 1.0000x reference)
.LBB0_246:
	s_mov_b32 s94, 0
	s_mov_b32 s95, 0
	s_mov_b32 s66, 0
	s_add_u32 s6, s96, 0x10000000
	s_addc_u32 s7, s97, 0
	s_mul_hi_i32 s9, s5, 0x5d800
	s_mul_i32 s5, s5, 0x5d800
	s_add_u32 s5, s96, s5
	s_addc_u32 s9, s97, s9
	s_add_u32 s53, s5, 0x24400000
	s_addc_u32 s54, s9, 0
	s_and_b32 s5, s8, 3
	s_add_i32 m0, s49, 0x18000
	v_lshl_add_u64 v[6:7], v[6:7], 0, s[34:35]
	s_lshl_b32 s10, s4, 13
	s_lshl_b32 s11, s5, 5
	s_lshl_b32 s12, s5, 12
	s_waitcnt vmcnt(2)
	s_barrier
	global_load_lds_dwordx4 v[6:7], off
	v_lshl_add_u64 v[4:5], v[4:5], 0, s[34:35]
	s_add_i32 m0, s49, 0x1a000
	s_add_i32 s55, s49, 0x8000
	s_add_i32 s56, s49, 0xa000
	global_load_lds_dwordx4 v[4:5], off
	v_lshl_add_u64 v[0:1], v[0:1], 0, s[34:35]
	s_mov_b32 m0, s55
	s_add_u32 s8, s20, 0x40080
	global_load_lds_dwordx4 v[0:1], off
	v_lshl_add_u64 v[0:1], v[2:3], 0, s[34:35]
	s_mov_b32 m0, s56
	s_addc_u32 s9, s21, 0
	global_load_lds_dwordx4 v[0:1], off
	s_add_i32 m0, s49, 0x1c000
	v_lshl_add_u64 v[0:1], s[8:9], 0, v[148:149]
	global_load_lds_dwordx4 v[0:1], off
	v_lshl_add_u64 v[0:1], s[8:9], 0, v[144:145]
	s_add_i32 m0, s49, 0x1e000
	s_cmpk_lt_u32 s3, 0x100
	global_load_lds_dwordx4 v[0:1], off
	s_sext_i32_i16 s60, s2
	v_bfe_u32 v2, v9, 4, 2
	s_cselect_b64 s[8:9], -1, 0
	s_and_b32 s2, s3, 0xffffff00
	s_lshl_b32 s3, s5, 6
	v_and_b32_e32 v1, 15, v9
	v_lshlrev_b32_e32 v0, 3, v2
	v_lshlrev_b32_e32 v2, 4, v2
	s_or_b32 s2, s3, s2
	v_lshl_or_b32 v166, s4, 6, v1
	v_lshl_or_b32 v3, v1, 6, v2
	v_or3_b32 v168, s2, v2, v1
	v_mov_b32_e32 v1, 0x20000
	v_lshl_add_u32 v169, v168, 2, v1
	v_lshlrev_b32_e32 v1, 14, v8
	v_and_b32_e32 v1, 0xffff8000, v1
	v_lshl_add_u32 v1, v10, 11, v1
	v_and_b32_e32 v2, 1, v8
	v_lshl_or_b32 v1, v2, 6, v1
	v_lshl_add_u32 v152, v11, 1, v1
	v_lshlrev_b32_e32 v1, 14, v13
	v_lshlrev_b32_e32 v4, 2, v166
	v_and_b32_e32 v1, 0xffff8000, v1
	v_and_b32_e32 v5, 32, v4
	v_lshlrev_b32_e32 v6, 2, v9
	s_waitcnt vmcnt(6)
	v_lshl_add_u32 v1, v12, 11, v1
	v_and_b32_e32 v2, 1, v13
	v_bitop3_b32 v5, v3, s10, v5 bitop3:0xde
	v_and_b32_e32 v6, 32, v6
	s_movk_i32 s2, 0x100
	v_lshl_or_b32 v1, v2, 6, v1
	v_bitop3_b32 v167, v3, s12, v6 bitop3:0xde
	v_cmp_gt_i32_e64 s[2:3], s2, v168
	v_add_u32_e32 v170, 0x20000, v4
	s_ashr_i32 s57, s26, 31
	v_or_b32_e32 v171, s11, v0
	v_mov_b32_e32 v153, v177
	v_lshl_add_u32 v154, v14, 1, v1
	v_mov_b32_e32 v155, v177
	s_mov_b32 s58, 0
	v_add_u32_e32 v172, 0, v5
	s_lshl_b32 s59, s11, 2
	v_lshlrev_b32_e32 v176, 2, v0
	s_barrier
	s_branch .LBB0_249

.LBB0_248:
	s_andn2_b64 vcc, exec, s[18:19]
	s_mov_b32 s60, s10
	s_mov_b32 s18, s12
	s_mov_b32 s95, s94
	s_mov_b64 s[20:21], s[16:17]
	s_mov_b64 s[22:23], s[14:15]
	s_cbranch_vccz .LBB0_260
.LBB0_249:
	s_add_i32 s58, s58, 1
	s_mul_i32 s4, s58, s57
	s_mul_hi_u32 s5, s58, s26
	s_add_i32 s5, s5, s4
	s_mul_i32 s4, s58, s26
	s_add_u32 s14, s4, s27
	s_addc_u32 s15, s5, s43
	s_mov_b32 s94, 0
	s_mov_b32 s66, 0
	s_cmp_eq_u32 s58, 12
	s_cbranch_scc0 .Lks_hdr_done
	s_cmpk_eq_i32 s44, 0xc60
	s_cbranch_scc0 .Lks_hdr_done
	s_cmpk_ge_u32 s27, 192
	s_cbranch_scc1 .Lks_hdr_done
	s_mov_b32 s94, 1
	s_cmpk_lt_u32 s27, 96
	s_cbranch_scc1 .Lks_hdr_done
	s_mov_b32 s94, 2
	s_movk_i32 s66, 0x400
	s_sub_u32 s14, s14, 96
	s_subb_u32 s15, s15, 0
.Lks_hdr_done:
	v_mov_b64_e32 v[0:1], s[44:45]
	v_cmp_ge_i64_e32 vcc, s[14:15], v[0:1]
	v_cmp_lt_i64_e64 s[4:5], s[14:15], v[0:1]
	s_cbranch_vccnz .LBB0_251
	s_ashr_i32 s10, s14, 31
	s_lshr_b32 s10, s10, 29
	s_add_i32 s10, s14, s10
	s_ashr_i32 s11, s10, 3
	s_and_b32 s10, s10, -8
	s_sub_i32 s10, s14, s10
	s_cmp_lt_i32 s10, 0
	s_cselect_b32 s12, s48, s42
	s_mul_i32 s10, s12, s10
	s_add_i32 s10, s10, s11
	s_mul_hi_i32 s11, s10, 0x2e8ba2e9
	s_lshr_b32 s12, s11, 31
	s_ashr_i32 s11, s11, 5
	s_add_i32 s11, s11, s12
	s_lshl_b32 s12, s11, 3
	s_sub_i32 s13, s28, s12
	s_min_i32 s13, s13, 8
	s_abs_i32 s14, s13
	v_cvt_f32_u32_e32 v0, s14
	s_sub_i32 s16, 0, s14
	s_mulk_i32 s11, 0xb0
	s_sub_i32 s11, s10, s11
	v_rcp_iflag_f32_e32 v0, v0
	s_abs_i32 s10, s11
	s_xor_b32 s15, s11, s13
	s_ashr_i32 s15, s15, 31
	v_mul_f32_e32 v0, 0x4f7ffffe, v0
	v_cvt_u32_f32_e32 v0, v0
	s_nop 0
	v_readfirstlane_b32 s17, v0
	s_mul_i32 s16, s16, s17
	s_mul_hi_u32 s16, s17, s16
	s_add_i32 s17, s17, s16
	s_mul_hi_u32 s16, s10, s17
	s_mul_i32 s17, s16, s14
	s_sub_i32 s10, s10, s17
	s_add_i32 s19, s16, 1
	s_sub_i32 s17, s10, s14
	s_cmp_ge_u32 s10, s14
	s_cselect_b32 s16, s19, s16
	s_cselect_b32 s10, s17, s10
	s_add_i32 s17, s16, 1
	s_cmp_ge_u32 s10, s14
	s_cselect_b32 s10, s17, s16
	s_xor_b32 s10, s10, s15
	s_sub_i32 s10, s10, s15
	s_mul_i32 s13, s10, s13
	s_sub_i32 s11, s11, s13
	s_add_i32 s12, s11, s12
.LBB0_251:
	s_ashr_i32 s13, s12, 31
	s_lshl_b64 s[14:15], s[12:13], 19
	s_add_u32 s14, s29, s14
	s_addc_u32 s15, s38, s15
	s_add_u32 s14, s14, s66
	s_addc_u32 s15, s15, 0
	s_and_b64 s[16:17], s[4:5], exec
	s_cselect_b32 s13, s15, s23
	s_cselect_b32 s19, s14, s22
	s_ashr_i32 s11, s10, 31
	s_lshl_b64 s[16:17], s[10:11], 19
	s_add_u32 s16, s39, s16
	s_addc_u32 s17, s40, s17
	s_add_u32 s16, s16, s66
	s_addc_u32 s17, s17, 0
	s_and_b64 s[24:25], s[4:5], exec
	s_cselect_b32 s11, s17, s21
	s_cselect_b32 s61, s16, s20
	s_add_u32 s62, s20, 0x100
	s_addc_u32 s63, s21, 0
	s_add_u32 s20, s22, 0x40080
	s_addc_u32 s21, s23, 0
	s_mov_b32 s68, -2
	s_cmp_lg_u32 s95, 0
	s_cselect_b32 s68, 6, s68
	s_add_u32 s22, s20, 0xfffc0080
	s_addc_u32 s23, s21, -1
	s_add_i32 s64, 0, 0x10000
	s_cmp_eq_u32 s68, 12
	s_cselect_b32 s25, s13, s23
	s_cselect_b32 s24, s19, s22
	s_cselect_b32 s23, s11, s63
	s_cselect_b32 s22, s61, s62
	s_lshl_b32 s74, s18, 8
	v_add_u32_e32 v178, s74, v168
	v_ashrrev_i32_e32 v179, 31, v178
	v_lshlrev_b64 v[178:179], 6, v[178:179]
	v_lshl_add_u64 v[178:179], s[70:71], 0, v[178:179]
	s_and_saveexec_b64 s[78:79], s[2:3]
	global_load_dwordx4 v[238:241], v[178:179], off
	global_load_dwordx4 v[242:245], v[178:179], off offset:16
	global_load_dwordx4 v[246:249], v[178:179], off offset:32
	global_load_dwordx4 v[250:253], v[178:179], off offset:48
	s_mov_b64 exec, s[78:79]
	s_add_i32 s69, 0, 0x14000
	v_add_u32_e32 v140, s64, v167
	v_add_u32_e32 v164, s69, v167
	ds_read_b128 v[48:51], v140
	ds_read_b128 v[56:59], v140 offset:1024
	ds_read_b128 v[136:139], v140 offset:2048
	ds_read_b128 v[140:143], v140 offset:3072
	ds_read_b128 v[156:159], v164
	ds_read_b128 v[160:163], v164 offset:1024
	ds_read_b128 v[182:185], v164 offset:2048
	ds_read_b128 v[186:189], v164 offset:3072
	v_lshl_add_u64 v[164:165], s[20:21], 0, v[154:155]
	s_add_i32 m0, s49, 0xc000
	ds_read_b128 v[190:193], v172
	ds_read_b128 v[194:197], v172 offset:1024
	ds_read_b128 v[198:201], v172 offset:2048
	ds_read_b128 v[202:205], v172 offset:3072
	ds_read_b128 v[206:209], v172 offset:4096
	ds_read_b128 v[210:213], v172 offset:5120
	ds_read_b128 v[228:231], v172 offset:6144
	ds_read_b128 v[232:235], v172 offset:7168
	global_load_lds_dwordx4 v[164:165], off
	v_lshl_add_u64 v[164:165], s[20:21], 0, v[152:153]
	s_add_i32 m0, s49, 0xe000
	s_nop 0
	global_load_lds_dwordx4 v[164:165], off
	s_waitcnt vmcnt(12)
	s_waitcnt lgkmcnt(0)
	s_barrier
	s_setprio 1
	v_mfma_f32_16x16x32_bf16 v[132:135], v[48:51], v[190:193], 0
	v_mfma_f32_16x16x32_bf16 v[124:127], v[136:139], v[190:193], 0
	v_mfma_f32_16x16x32_bf16 v[116:119], v[48:51], v[198:201], 0
	v_mfma_f32_16x16x32_bf16 v[112:115], v[136:139], v[198:201], 0
	v_mfma_f32_16x16x32_bf16 v[100:103], v[48:51], v[206:209], 0
	v_mfma_f32_16x16x32_bf16 v[96:99], v[136:139], v[206:209], 0
	v_mfma_f32_16x16x32_bf16 v[84:87], v[48:51], v[228:231], 0
	v_mfma_f32_16x16x32_bf16 v[80:83], v[136:139], v[228:231], 0
	v_mfma_f32_16x16x32_bf16 v[132:135], v[56:59], v[194:197], v[132:135]
	v_mfma_f32_16x16x32_bf16 v[124:127], v[140:143], v[194:197], v[124:127]
	v_mfma_f32_16x16x32_bf16 v[116:119], v[56:59], v[202:205], v[116:119]
	v_mfma_f32_16x16x32_bf16 v[112:115], v[140:143], v[202:205], v[112:115]
	v_mfma_f32_16x16x32_bf16 v[100:103], v[56:59], v[210:213], v[100:103]
	v_mfma_f32_16x16x32_bf16 v[96:99], v[140:143], v[210:213], v[96:99]
	v_mfma_f32_16x16x32_bf16 v[84:87], v[56:59], v[232:235], v[84:87]
	v_mfma_f32_16x16x32_bf16 v[80:83], v[140:143], v[232:235], v[80:83]
	v_mfma_f32_16x16x32_bf16 v[128:131], v[156:159], v[190:193], 0
	v_mfma_f32_16x16x32_bf16 v[120:123], v[182:185], v[190:193], 0
	v_mfma_f32_16x16x32_bf16 v[108:111], v[156:159], v[198:201], 0
	v_mfma_f32_16x16x32_bf16 v[104:107], v[182:185], v[198:201], 0
	v_mfma_f32_16x16x32_bf16 v[92:95], v[156:159], v[206:209], 0
	v_mfma_f32_16x16x32_bf16 v[88:91], v[182:185], v[206:209], 0
	v_mfma_f32_16x16x32_bf16 v[76:79], v[156:159], v[228:231], 0
	v_mfma_f32_16x16x32_bf16 v[72:75], v[182:185], v[228:231], 0
	v_mfma_f32_16x16x32_bf16 v[128:131], v[160:163], v[194:197], v[128:131]
	v_mfma_f32_16x16x32_bf16 v[120:123], v[186:189], v[194:197], v[120:123]
	v_mfma_f32_16x16x32_bf16 v[108:111], v[160:163], v[202:205], v[108:111]
	v_mfma_f32_16x16x32_bf16 v[104:107], v[186:189], v[202:205], v[104:107]
	s_setprio 2
	s_barrier
	v_mfma_f32_16x16x32_bf16 v[92:95], v[160:163], v[210:213], v[92:95]
	v_mfma_f32_16x16x32_bf16 v[88:91], v[186:189], v[210:213], v[88:91]
	v_mfma_f32_16x16x32_bf16 v[76:79], v[160:163], v[232:235], v[76:79]
	v_mfma_f32_16x16x32_bf16 v[72:75], v[186:189], v[232:235], v[72:75]
	s_setprio 0
	s_add_i32 s64, s64, s41
	v_lshl_add_u64 v[164:165], s[22:23], 0, v[148:149]
	s_mov_b32 m0, s64
	ds_read_b128 v[190:193], v172 offset:16384
	ds_read_b128 v[194:197], v172 offset:17408
	ds_read_b128 v[198:201], v172 offset:18432
	ds_read_b128 v[202:205], v172 offset:19456
	ds_read_b128 v[206:209], v172 offset:20480
	ds_read_b128 v[210:213], v172 offset:21504
	ds_read_b128 v[228:231], v172 offset:22528
	ds_read_b128 v[232:235], v172 offset:23552
	global_load_lds_dwordx4 v[164:165], off
	s_add_i32 m0, s64, 0x2000
	s_add_u32 s64, s22, 0x40000
	v_lshl_add_u64 v[220:221], s[22:23], 0, v[144:145]
	s_addc_u32 s65, s23, 0
	s_add_i32 s69, s69, s41
	global_load_lds_dwordx4 v[220:221], off
	v_lshl_add_u64 v[222:223], s[64:65], 0, v[148:149]
	s_mov_b32 m0, s69
	v_lshl_add_u64 v[226:227], s[24:25], 0, v[146:147]
	global_load_lds_dwordx4 v[222:223], off
	v_lshl_add_u64 v[222:223], s[64:65], 0, v[144:145]
	s_add_i32 m0, s69, 0x2000
	s_nop 0
	global_load_lds_dwordx4 v[222:223], off
	v_lshl_add_u64 v[222:223], s[24:25], 0, v[150:151]
	s_mov_b32 m0, s49
	s_nop 0
	global_load_lds_dwordx4 v[222:223], off
	s_mov_b32 m0, s50
	s_nop 0
	global_load_lds_dwordx4 v[226:227], off
	s_waitcnt vmcnt(8)
	s_waitcnt lgkmcnt(0)
	s_barrier
	s_setprio 1
	v_mfma_f32_16x16x32_bf16 v[68:71], v[48:51], v[190:193], 0
	v_mfma_f32_16x16x32_bf16 v[64:67], v[136:139], v[190:193], 0
	v_mfma_f32_16x16x32_bf16 v[44:47], v[48:51], v[198:201], 0
	v_mfma_f32_16x16x32_bf16 v[40:43], v[136:139], v[198:201], 0
	v_mfma_f32_16x16x32_bf16 v[28:31], v[48:51], v[206:209], 0
	v_mfma_f32_16x16x32_bf16 v[24:27], v[136:139], v[206:209], 0
	v_mfma_f32_16x16x32_bf16 v[12:15], v[48:51], v[228:231], 0
	v_mfma_f32_16x16x32_bf16 v[8:11], v[136:139], v[228:231], 0
	v_mfma_f32_16x16x32_bf16 v[68:71], v[56:59], v[194:197], v[68:71]
	v_mfma_f32_16x16x32_bf16 v[64:67], v[140:143], v[194:197], v[64:67]
	v_mfma_f32_16x16x32_bf16 v[44:47], v[56:59], v[202:205], v[44:47]
	v_mfma_f32_16x16x32_bf16 v[40:43], v[140:143], v[202:205], v[40:43]
	v_mfma_f32_16x16x32_bf16 v[28:31], v[56:59], v[210:213], v[28:31]
	v_mfma_f32_16x16x32_bf16 v[24:27], v[140:143], v[210:213], v[24:27]
	v_mfma_f32_16x16x32_bf16 v[12:15], v[56:59], v[232:235], v[12:15]
	v_mfma_f32_16x16x32_bf16 v[8:11], v[140:143], v[232:235], v[8:11]
	v_mfma_f32_16x16x32_bf16 v[52:55], v[182:185], v[190:193], 0
	v_mfma_f32_16x16x32_bf16 v[36:39], v[156:159], v[198:201], 0
	v_mfma_f32_16x16x32_bf16 v[32:35], v[182:185], v[198:201], 0
	v_mfma_f32_16x16x32_bf16 v[20:23], v[156:159], v[206:209], 0
	v_mfma_f32_16x16x32_bf16 v[16:19], v[182:185], v[206:209], 0
	v_mfma_f32_16x16x32_bf16 v[4:7], v[156:159], v[228:231], 0
	v_mfma_f32_16x16x32_bf16 v[0:3], v[182:185], v[228:231], 0
	v_mfma_f32_16x16x32_bf16 v[48:51], v[156:159], v[190:193], 0
	v_mfma_f32_16x16x32_bf16 v[52:55], v[186:189], v[194:197], v[52:55]
	v_mfma_f32_16x16x32_bf16 v[36:39], v[160:163], v[202:205], v[36:39]
	v_mfma_f32_16x16x32_bf16 v[32:35], v[186:189], v[202:205], v[32:35]
	v_mfma_f32_16x16x32_bf16 v[20:23], v[160:163], v[210:213], v[20:23]
	s_setprio 2
	s_barrier
	v_mfma_f32_16x16x32_bf16 v[16:19], v[186:189], v[210:213], v[16:19]
	v_mfma_f32_16x16x32_bf16 v[4:7], v[160:163], v[232:235], v[4:7]
	v_mfma_f32_16x16x32_bf16 v[0:3], v[186:189], v[232:235], v[0:3]
	v_mfma_f32_16x16x32_bf16 v[48:51], v[160:163], v[194:197], v[48:51]
	s_setprio 0
	s_and_saveexec_b64 s[78:79], s[2:3]
	v_add_f32_e32 v238, v238, v239
	v_add_f32_e32 v240, v240, v241
	v_add_f32_e32 v242, v242, v243
	v_add_f32_e32 v244, v244, v245
	v_add_f32_e32 v246, v246, v247
	v_add_f32_e32 v248, v248, v249
	v_add_f32_e32 v250, v250, v251
	v_add_f32_e32 v252, v252, v253
	v_add_f32_e32 v238, v238, v240
	v_add_f32_e32 v242, v242, v244
	v_add_f32_e32 v246, v246, v248
	v_add_f32_e32 v250, v250, v252
	v_add_f32_e32 v238, v238, v242
	v_add_f32_e32 v246, v246, v250
	v_add_f32_e32 v238, v238, v246
	v_fmamk_f32 v238, v238, 0x3a800000, v216
	v_rsq_f32_e32 v238, v238
	s_nop 0
	ds_write_b32 v169, v238
	s_mov_b64 exec, s[78:79]
	s_add_i32 s64, 0, 0x18000
	s_add_i32 s65, 0, 0x1c000
	v_add_u32_e32 v140, s64, v167
	v_add_u32_e32 v173, s65, v167
	ds_read_b128 v[56:59], v140
	ds_read_b128 v[60:63], v140 offset:1024
	ds_read_b128 v[136:139], v140 offset:2048
	ds_read_b128 v[140:143], v140 offset:3072
	ds_read_b128 v[156:159], v173
	ds_read_b128 v[160:163], v173 offset:1024
	ds_read_b128 v[182:185], v173 offset:2048
	ds_read_b128 v[186:189], v173 offset:3072
	s_add_u32 s24, s24, 0x40000
	s_addc_u32 s25, s25, 0
	s_mov_b32 m0, s51
	v_lshl_add_u64 v[236:237], s[24:25], 0, v[150:151]
	ds_read_b128 v[190:193], v172 offset:32768
	ds_read_b128 v[194:197], v172 offset:33792
	ds_read_b128 v[198:201], v172 offset:34816
	ds_read_b128 v[202:205], v172 offset:35840
	ds_read_b128 v[206:209], v172 offset:36864
	ds_read_b128 v[210:213], v172 offset:37888
	ds_read_b128 v[228:231], v172 offset:38912
	ds_read_b128 v[232:235], v172 offset:39936
	global_load_lds_dwordx4 v[236:237], off
	v_lshl_add_u64 v[236:237], s[24:25], 0, v[146:147]
	s_mov_b32 m0, s52
	s_nop 0
	global_load_lds_dwordx4 v[236:237], off
	s_waitcnt vmcnt(8)
	s_waitcnt lgkmcnt(0)
	s_barrier
	s_setprio 1
	v_mfma_f32_16x16x32_bf16 v[132:135], v[56:59], v[190:193], v[132:135]
	v_mfma_f32_16x16x32_bf16 v[124:127], v[136:139], v[190:193], v[124:127]
	v_mfma_f32_16x16x32_bf16 v[116:119], v[56:59], v[198:201], v[116:119]
	v_mfma_f32_16x16x32_bf16 v[112:115], v[136:139], v[198:201], v[112:115]
	v_mfma_f32_16x16x32_bf16 v[100:103], v[56:59], v[206:209], v[100:103]
	v_mfma_f32_16x16x32_bf16 v[96:99], v[136:139], v[206:209], v[96:99]
	v_mfma_f32_16x16x32_bf16 v[84:87], v[56:59], v[228:231], v[84:87]
	v_mfma_f32_16x16x32_bf16 v[80:83], v[136:139], v[228:231], v[80:83]
	v_mfma_f32_16x16x32_bf16 v[132:135], v[60:63], v[194:197], v[132:135]
	v_mfma_f32_16x16x32_bf16 v[124:127], v[140:143], v[194:197], v[124:127]
	v_mfma_f32_16x16x32_bf16 v[116:119], v[60:63], v[202:205], v[116:119]
	v_mfma_f32_16x16x32_bf16 v[112:115], v[140:143], v[202:205], v[112:115]
	v_mfma_f32_16x16x32_bf16 v[100:103], v[60:63], v[210:213], v[100:103]
	v_mfma_f32_16x16x32_bf16 v[96:99], v[140:143], v[210:213], v[96:99]
	v_mfma_f32_16x16x32_bf16 v[84:87], v[60:63], v[232:235], v[84:87]
	v_mfma_f32_16x16x32_bf16 v[80:83], v[140:143], v[232:235], v[80:83]
	v_mfma_f32_16x16x32_bf16 v[128:131], v[156:159], v[190:193], v[128:131]
	v_mfma_f32_16x16x32_bf16 v[120:123], v[182:185], v[190:193], v[120:123]
	v_mfma_f32_16x16x32_bf16 v[108:111], v[156:159], v[198:201], v[108:111]
	v_mfma_f32_16x16x32_bf16 v[104:107], v[182:185], v[198:201], v[104:107]
	v_mfma_f32_16x16x32_bf16 v[92:95], v[156:159], v[206:209], v[92:95]
	v_mfma_f32_16x16x32_bf16 v[88:91], v[182:185], v[206:209], v[88:91]
	v_mfma_f32_16x16x32_bf16 v[76:79], v[156:159], v[228:231], v[76:79]
	v_mfma_f32_16x16x32_bf16 v[72:75], v[182:185], v[228:231], v[72:75]
	v_mfma_f32_16x16x32_bf16 v[128:131], v[160:163], v[194:197], v[128:131]
	v_mfma_f32_16x16x32_bf16 v[120:123], v[186:189], v[194:197], v[120:123]
	v_mfma_f32_16x16x32_bf16 v[108:111], v[160:163], v[202:205], v[108:111]
	v_mfma_f32_16x16x32_bf16 v[104:107], v[186:189], v[202:205], v[104:107]
	s_setprio 2
	s_barrier
	v_mfma_f32_16x16x32_bf16 v[92:95], v[160:163], v[210:213], v[92:95]
	v_mfma_f32_16x16x32_bf16 v[88:91], v[186:189], v[210:213], v[88:91]
	v_mfma_f32_16x16x32_bf16 v[76:79], v[160:163], v[232:235], v[76:79]
	v_mfma_f32_16x16x32_bf16 v[72:75], v[186:189], v[232:235], v[72:75]
	s_setprio 0
	s_min_i32 s74, s18, 0x80
	s_ashr_i32 s74, s74, 3
	s_mul_hi_i32 s75, s74, 0x5800
	s_mulk_i32 s74, 0x5800
	s_add_u32 s74, s53, s74
	s_addc_u32 s75, s54, s75
	s_lshl_b32 s76, s60, 8
	s_ashr_i32 s77, s76, 31
	s_lshl_b64 s[76:77], s[76:77], 2
	s_add_u32 s74, s74, s76
	s_addc_u32 s75, s75, s77
	s_add_u32 s74, s74, s59
	s_addc_u32 s75, s75, 0
	v_lshl_add_u64 v[178:179], s[74:75], 0, v[176:177]
	global_load_dwordx4 v[238:241], v[178:179], off
	global_load_dwordx4 v[242:245], v[178:179], off offset:16
	global_load_dwordx4 v[246:249], v[178:179], off offset:512
	global_load_dwordx4 v[250:253], v[178:179], off offset:528
	s_add_i32 s24, s64, s41
	v_lshl_add_u64 v[164:165], v[164:165], 0, s[34:35]
	s_mov_b32 m0, s24
	ds_read_b128 v[190:193], v172 offset:49152
	ds_read_b128 v[194:197], v172 offset:50176
	ds_read_b128 v[198:201], v172 offset:51200
	ds_read_b128 v[202:205], v172 offset:52224
	ds_read_b128 v[206:209], v172 offset:53248
	ds_read_b128 v[210:213], v172 offset:54272
	ds_read_b128 v[228:231], v172 offset:55296
	ds_read_b128 v[232:235], v172 offset:56320
	global_load_lds_dwordx4 v[164:165], off
	s_add_i32 m0, s24, 0x2000
	s_add_u32 s22, s22, 0x40080
	v_lshl_add_u64 v[164:165], v[220:221], 0, s[34:35]
	s_addc_u32 s23, s23, 0
	s_add_i32 s24, s65, s41
	global_load_lds_dwordx4 v[164:165], off
	v_lshl_add_u64 v[164:165], s[22:23], 0, v[148:149]
	s_mov_b32 m0, s24
	s_nop 0
	global_load_lds_dwordx4 v[164:165], off
	v_lshl_add_u64 v[164:165], s[22:23], 0, v[144:145]
	s_add_i32 m0, s24, 0x2000
	s_nop 0
	global_load_lds_dwordx4 v[164:165], off
	v_lshl_add_u64 v[164:165], v[222:223], 0, s[34:35]
	s_mov_b32 m0, s55
	s_nop 0
	global_load_lds_dwordx4 v[164:165], off
	v_lshl_add_u64 v[164:165], v[226:227], 0, s[34:35]
	s_mov_b32 m0, s56
	s_nop 0
	global_load_lds_dwordx4 v[164:165], off
	s_waitcnt vmcnt(12)
	s_waitcnt lgkmcnt(0)
	s_barrier
	s_setprio 1
	v_mfma_f32_16x16x32_bf16 v[68:71], v[56:59], v[190:193], v[68:71]
	v_mfma_f32_16x16x32_bf16 v[64:67], v[136:139], v[190:193], v[64:67]
	v_mfma_f32_16x16x32_bf16 v[44:47], v[56:59], v[198:201], v[44:47]
	v_mfma_f32_16x16x32_bf16 v[40:43], v[136:139], v[198:201], v[40:43]
	v_mfma_f32_16x16x32_bf16 v[28:31], v[56:59], v[206:209], v[28:31]
	v_mfma_f32_16x16x32_bf16 v[24:27], v[136:139], v[206:209], v[24:27]
	v_mfma_f32_16x16x32_bf16 v[12:15], v[56:59], v[228:231], v[12:15]
	v_mfma_f32_16x16x32_bf16 v[8:11], v[136:139], v[228:231], v[8:11]
	v_mfma_f32_16x16x32_bf16 v[68:71], v[60:63], v[194:197], v[68:71]
	v_mfma_f32_16x16x32_bf16 v[64:67], v[140:143], v[194:197], v[64:67]
	v_mfma_f32_16x16x32_bf16 v[44:47], v[60:63], v[202:205], v[44:47]
	v_mfma_f32_16x16x32_bf16 v[40:43], v[140:143], v[202:205], v[40:43]
	v_mfma_f32_16x16x32_bf16 v[28:31], v[60:63], v[210:213], v[28:31]
	v_mfma_f32_16x16x32_bf16 v[24:27], v[140:143], v[210:213], v[24:27]
	v_mfma_f32_16x16x32_bf16 v[12:15], v[60:63], v[232:235], v[12:15]
	v_mfma_f32_16x16x32_bf16 v[8:11], v[140:143], v[232:235], v[8:11]
	v_mfma_f32_16x16x32_bf16 v[48:51], v[156:159], v[190:193], v[48:51]
	v_mfma_f32_16x16x32_bf16 v[60:63], v[160:163], v[194:197], v[48:51]
	v_mfma_f32_16x16x32_bf16 v[48:51], v[182:185], v[190:193], v[52:55]
	v_mfma_f32_16x16x32_bf16 v[36:39], v[156:159], v[198:201], v[36:39]
	v_mfma_f32_16x16x32_bf16 v[32:35], v[182:185], v[198:201], v[32:35]
	v_mfma_f32_16x16x32_bf16 v[20:23], v[156:159], v[206:209], v[20:23]
	v_mfma_f32_16x16x32_bf16 v[16:19], v[182:185], v[206:209], v[16:19]
	v_mfma_f32_16x16x32_bf16 v[4:7], v[156:159], v[228:231], v[4:7]
	v_mfma_f32_16x16x32_bf16 v[0:3], v[182:185], v[228:231], v[0:3]
	v_mfma_f32_16x16x32_bf16 v[52:55], v[186:189], v[194:197], v[48:51]
	v_mfma_f32_16x16x32_bf16 v[36:39], v[160:163], v[202:205], v[36:39]
	v_mfma_f32_16x16x32_bf16 v[32:35], v[186:189], v[202:205], v[32:35]
	s_setprio 2
	s_barrier
	v_mfma_f32_16x16x32_bf16 v[20:23], v[160:163], v[210:213], v[20:23]
	v_mfma_f32_16x16x32_bf16 v[16:19], v[186:189], v[210:213], v[16:19]
	v_mfma_f32_16x16x32_bf16 v[4:7], v[160:163], v[232:235], v[4:7]
	v_mfma_f32_16x16x32_bf16 v[0:3], v[186:189], v[232:235], v[0:3]
	s_setprio 0
	s_add_i32 s68, s68, 2
	s_add_u32 s62, s62, 0x100
	s_addc_u32 s63, s63, 0
	s_add_u32 s20, s20, 0x100
	s_addc_u32 s21, s21, 0
	s_cmp_gt_u32 s68, 13

.LBB0_255:
	s_lshl_b32 s11, s18, 8
	s_mov_b64 s[18:19], -1
	s_cmp_eq_u32 s95, 0
	s_cbranch_scc1 .Lks_normal
	s_mov_b32 s74, s27
	s_cmp_eq_u32 s95, 2
	s_cbranch_scc0 .Lks_slot
	s_sub_i32 s74, s74, 96
.Lks_slot:
	s_lshl_b32 s75, s74, 6
	s_add_u32 s76, s96, 0x608000
	s_addc_u32 s77, s97, 0
	s_add_u32 s76, s76, s75
	s_addc_u32 s77, s77, 0
	s_lshl_b32 s75, s74, 18
	s_add_u32 s78, s96, 0x1c800000
	s_addc_u32 s79, s97, 0
	s_add_u32 s78, s78, s75
	s_addc_u32 s79, s79, 0
	s_lshl_b32 s75, s49, 5
	s_add_u32 s78, s78, s75
	s_addc_u32 s79, s79, 0
	v_mbcnt_lo_u32_b32 v178, -1, 0
	v_mbcnt_hi_u32_b32 v178, -1, v178
	v_lshlrev_b32_e32 v178, 4, v178
	v_mov_b32_e32 v179, 0
	v_mov_b32_e32 v180, 1
	s_cmp_eq_u32 s95, 2
	s_cbranch_scc1 .Lks_helper
	s_cmp_lg_u32 s49, 0
	s_cbranch_scc1 .Lks_own_wait
	s_mov_b64 exec, 1
.Lks_poll:
	global_load_dword v175, v179, s[76:77] sc1
	s_waitcnt vmcnt(0)
	v_readfirstlane_b32 s80, v175
	s_cmp_lg_u32 s80, 0
	s_cbranch_scc1 .Lks_got
	s_sleep 2
	s_branch .Lks_poll
.Lks_got:
	v_mov_b32_e32 v175, -1
	global_atomic_add v179, v175, s[76:77]
	s_mov_b64 exec, -1
.Lks_own_wait:
	s_barrier
	buffer_inv sc1
	global_load_dwordx4 v[48:51], v178, s[78:79] offset:0
	global_load_dwordx4 v[56:59], v178, s[78:79] offset:1024
	global_load_dwordx4 v[136:139], v178, s[78:79] offset:2048
	global_load_dwordx4 v[140:143], v178, s[78:79] offset:3072
	s_add_u32 s78, s78, 0x1000
	s_addc_u32 s79, s79, 0
	global_load_dwordx4 v[156:159], v178, s[78:79] offset:0
	global_load_dwordx4 v[160:163], v178, s[78:79] offset:1024
	global_load_dwordx4 v[182:185], v178, s[78:79] offset:2048
	global_load_dwordx4 v[186:189], v178, s[78:79] offset:3072
	s_waitcnt vmcnt(0)
	v_add_f32_e32 v132, v132, v48
	v_add_f32_e32 v133, v133, v49
	v_add_f32_e32 v134, v134, v50
	v_add_f32_e32 v135, v135, v51
	v_add_f32_e32 v124, v124, v56
	v_add_f32_e32 v125, v125, v57
	v_add_f32_e32 v126, v126, v58
	v_add_f32_e32 v127, v127, v59
	v_add_f32_e32 v128, v128, v136
	v_add_f32_e32 v129, v129, v137
	v_add_f32_e32 v130, v130, v138
	v_add_f32_e32 v131, v131, v139
	v_add_f32_e32 v120, v120, v140
	v_add_f32_e32 v121, v121, v141
	v_add_f32_e32 v122, v122, v142
	v_add_f32_e32 v123, v123, v143
	v_add_f32_e32 v116, v116, v156
	v_add_f32_e32 v117, v117, v157
	v_add_f32_e32 v118, v118, v158
	v_add_f32_e32 v119, v119, v159
	v_add_f32_e32 v112, v112, v160
	v_add_f32_e32 v113, v113, v161
	v_add_f32_e32 v114, v114, v162
	v_add_f32_e32 v115, v115, v163
	v_add_f32_e32 v108, v108, v182
	v_add_f32_e32 v109, v109, v183
	v_add_f32_e32 v110, v110, v184
	v_add_f32_e32 v111, v111, v185
	v_add_f32_e32 v104, v104, v186
	v_add_f32_e32 v105, v105, v187
	v_add_f32_e32 v106, v106, v188
	v_add_f32_e32 v107, v107, v189
	s_add_u32 s78, s78, 0x1000
	s_addc_u32 s79, s79, 0
	global_load_dwordx4 v[48:51], v178, s[78:79] offset:0
	global_load_dwordx4 v[56:59], v178, s[78:79] offset:1024
	global_load_dwordx4 v[136:139], v178, s[78:79] offset:2048
	global_load_dwordx4 v[140:143], v178, s[78:79] offset:3072
	s_add_u32 s78, s78, 0x1000
	s_addc_u32 s79, s79, 0
	global_load_dwordx4 v[156:159], v178, s[78:79] offset:0
	global_load_dwordx4 v[160:163], v178, s[78:79] offset:1024
	global_load_dwordx4 v[182:185], v178, s[78:79] offset:2048
	global_load_dwordx4 v[186:189], v178, s[78:79] offset:3072
	s_waitcnt vmcnt(0)
	v_add_f32_e32 v100, v100, v48
	v_add_f32_e32 v101, v101, v49
	v_add_f32_e32 v102, v102, v50
	v_add_f32_e32 v103, v103, v51
	v_add_f32_e32 v96, v96, v56
	v_add_f32_e32 v97, v97, v57
	v_add_f32_e32 v98, v98, v58
	v_add_f32_e32 v99, v99, v59
	v_add_f32_e32 v92, v92, v136
	v_add_f32_e32 v93, v93, v137
	v_add_f32_e32 v94, v94, v138
	v_add_f32_e32 v95, v95, v139
	v_add_f32_e32 v88, v88, v140
	v_add_f32_e32 v89, v89, v141
	v_add_f32_e32 v90, v90, v142
	v_add_f32_e32 v91, v91, v143
	v_add_f32_e32 v84, v84, v156
	v_add_f32_e32 v85, v85, v157
	v_add_f32_e32 v86, v86, v158
	v_add_f32_e32 v87, v87, v159
	v_add_f32_e32 v80, v80, v160
	v_add_f32_e32 v81, v81, v161
	v_add_f32_e32 v82, v82, v162
	v_add_f32_e32 v83, v83, v163
	v_add_f32_e32 v76, v76, v182
	v_add_f32_e32 v77, v77, v183
	v_add_f32_e32 v78, v78, v184
	v_add_f32_e32 v79, v79, v185
	v_add_f32_e32 v72, v72, v186
	v_add_f32_e32 v73, v73, v187
	v_add_f32_e32 v74, v74, v188
	v_add_f32_e32 v75, v75, v189
	s_add_u32 s78, s78, 0x1000
	s_addc_u32 s79, s79, 0
	global_load_dwordx4 v[48:51], v178, s[78:79] offset:0
	global_load_dwordx4 v[56:59], v178, s[78:79] offset:1024
	global_load_dwordx4 v[136:139], v178, s[78:79] offset:2048
	global_load_dwordx4 v[140:143], v178, s[78:79] offset:3072
	s_add_u32 s78, s78, 0x1000
	s_addc_u32 s79, s79, 0
	global_load_dwordx4 v[156:159], v178, s[78:79] offset:0
	global_load_dwordx4 v[160:163], v178, s[78:79] offset:1024
	global_load_dwordx4 v[182:185], v178, s[78:79] offset:2048
	global_load_dwordx4 v[186:189], v178, s[78:79] offset:3072
	s_waitcnt vmcnt(0)
	v_add_f32_e32 v68, v68, v48
	v_add_f32_e32 v69, v69, v49
	v_add_f32_e32 v70, v70, v50
	v_add_f32_e32 v71, v71, v51
	v_add_f32_e32 v64, v64, v56
	v_add_f32_e32 v65, v65, v57
	v_add_f32_e32 v66, v66, v58
	v_add_f32_e32 v67, v67, v59
	v_add_f32_e32 v60, v60, v136
	v_add_f32_e32 v61, v61, v137
	v_add_f32_e32 v62, v62, v138
	v_add_f32_e32 v63, v63, v139
	v_add_f32_e32 v52, v52, v140
	v_add_f32_e32 v53, v53, v141
	v_add_f32_e32 v54, v54, v142
	v_add_f32_e32 v55, v55, v143
	v_add_f32_e32 v44, v44, v156
	v_add_f32_e32 v45, v45, v157
	v_add_f32_e32 v46, v46, v158
	v_add_f32_e32 v47, v47, v159
	v_add_f32_e32 v40, v40, v160
	v_add_f32_e32 v41, v41, v161
	v_add_f32_e32 v42, v42, v162
	v_add_f32_e32 v43, v43, v163
	v_add_f32_e32 v36, v36, v182
	v_add_f32_e32 v37, v37, v183
	v_add_f32_e32 v38, v38, v184
	v_add_f32_e32 v39, v39, v185
	v_add_f32_e32 v32, v32, v186
	v_add_f32_e32 v33, v33, v187
	v_add_f32_e32 v34, v34, v188
	v_add_f32_e32 v35, v35, v189
	s_add_u32 s78, s78, 0x1000
	s_addc_u32 s79, s79, 0
	global_load_dwordx4 v[48:51], v178, s[78:79] offset:0
	global_load_dwordx4 v[56:59], v178, s[78:79] offset:1024
	global_load_dwordx4 v[136:139], v178, s[78:79] offset:2048
	global_load_dwordx4 v[140:143], v178, s[78:79] offset:3072
	s_add_u32 s78, s78, 0x1000
	s_addc_u32 s79, s79, 0
	global_load_dwordx4 v[156:159], v178, s[78:79] offset:0
	global_load_dwordx4 v[160:163], v178, s[78:79] offset:1024
	global_load_dwordx4 v[182:185], v178, s[78:79] offset:2048
	global_load_dwordx4 v[186:189], v178, s[78:79] offset:3072
	s_waitcnt vmcnt(0)
	v_add_f32_e32 v28, v28, v48
	v_add_f32_e32 v29, v29, v49
	v_add_f32_e32 v30, v30, v50
	v_add_f32_e32 v31, v31, v51
	v_add_f32_e32 v24, v24, v56
	v_add_f32_e32 v25, v25, v57
	v_add_f32_e32 v26, v26, v58
	v_add_f32_e32 v27, v27, v59
	v_add_f32_e32 v20, v20, v136
	v_add_f32_e32 v21, v21, v137
	v_add_f32_e32 v22, v22, v138
	v_add_f32_e32 v23, v23, v139
	v_add_f32_e32 v16, v16, v140
	v_add_f32_e32 v17, v17, v141
	v_add_f32_e32 v18, v18, v142
	v_add_f32_e32 v19, v19, v143
	v_add_f32_e32 v12, v12, v156
	v_add_f32_e32 v13, v13, v157
	v_add_f32_e32 v14, v14, v158
	v_add_f32_e32 v15, v15, v159
	v_add_f32_e32 v8, v8, v160
	v_add_f32_e32 v9, v9, v161
	v_add_f32_e32 v10, v10, v162
	v_add_f32_e32 v11, v11, v163
	v_add_f32_e32 v4, v4, v182
	v_add_f32_e32 v5, v5, v183
	v_add_f32_e32 v6, v6, v184
	v_add_f32_e32 v7, v7, v185
	v_add_f32_e32 v0, v0, v186
	v_add_f32_e32 v1, v1, v187
	v_add_f32_e32 v2, v2, v188
	v_add_f32_e32 v3, v3, v189
	s_branch .Lks_normal
.Lks_helper:
	global_store_dwordx4 v178, v[132:135], s[78:79] offset:0 sc0 sc1
	global_store_dwordx4 v178, v[124:127], s[78:79] offset:1024 sc0 sc1
	global_store_dwordx4 v178, v[128:131], s[78:79] offset:2048 sc0 sc1
	global_store_dwordx4 v178, v[120:123], s[78:79] offset:3072 sc0 sc1
	s_add_u32 s78, s78, 0x1000
	s_addc_u32 s79, s79, 0
	global_store_dwordx4 v178, v[116:119], s[78:79] offset:0 sc0 sc1
	global_store_dwordx4 v178, v[112:115], s[78:79] offset:1024 sc0 sc1
	global_store_dwordx4 v178, v[108:111], s[78:79] offset:2048 sc0 sc1
	global_store_dwordx4 v178, v[104:107], s[78:79] offset:3072 sc0 sc1
	s_add_u32 s78, s78, 0x1000
	s_addc_u32 s79, s79, 0
	global_store_dwordx4 v178, v[100:103], s[78:79] offset:0 sc0 sc1
	global_store_dwordx4 v178, v[96:99], s[78:79] offset:1024 sc0 sc1
	global_store_dwordx4 v178, v[92:95], s[78:79] offset:2048 sc0 sc1
	global_store_dwordx4 v178, v[88:91], s[78:79] offset:3072 sc0 sc1
	s_add_u32 s78, s78, 0x1000
	s_addc_u32 s79, s79, 0
	global_store_dwordx4 v178, v[84:87], s[78:79] offset:0 sc0 sc1
	global_store_dwordx4 v178, v[80:83], s[78:79] offset:1024 sc0 sc1
	global_store_dwordx4 v178, v[76:79], s[78:79] offset:2048 sc0 sc1
	global_store_dwordx4 v178, v[72:75], s[78:79] offset:3072 sc0 sc1
	s_add_u32 s78, s78, 0x1000
	s_addc_u32 s79, s79, 0
	global_store_dwordx4 v178, v[68:71], s[78:79] offset:0 sc0 sc1
	global_store_dwordx4 v178, v[64:67], s[78:79] offset:1024 sc0 sc1
	global_store_dwordx4 v178, v[60:63], s[78:79] offset:2048 sc0 sc1
	global_store_dwordx4 v178, v[52:55], s[78:79] offset:3072 sc0 sc1
	s_add_u32 s78, s78, 0x1000
	s_addc_u32 s79, s79, 0
	global_store_dwordx4 v178, v[44:47], s[78:79] offset:0 sc0 sc1
	global_store_dwordx4 v178, v[40:43], s[78:79] offset:1024 sc0 sc1
	global_store_dwordx4 v178, v[36:39], s[78:79] offset:2048 sc0 sc1
	global_store_dwordx4 v178, v[32:35], s[78:79] offset:3072 sc0 sc1
	s_add_u32 s78, s78, 0x1000
	s_addc_u32 s79, s79, 0
	global_store_dwordx4 v178, v[28:31], s[78:79] offset:0 sc0 sc1
	global_store_dwordx4 v178, v[24:27], s[78:79] offset:1024 sc0 sc1
	global_store_dwordx4 v178, v[20:23], s[78:79] offset:2048 sc0 sc1
	global_store_dwordx4 v178, v[16:19], s[78:79] offset:3072 sc0 sc1
	s_add_u32 s78, s78, 0x1000
	s_addc_u32 s79, s79, 0
	global_store_dwordx4 v178, v[12:15], s[78:79] offset:0 sc0 sc1
	global_store_dwordx4 v178, v[8:11], s[78:79] offset:1024 sc0 sc1
	global_store_dwordx4 v178, v[4:7], s[78:79] offset:2048 sc0 sc1
	global_store_dwordx4 v178, v[0:3], s[78:79] offset:3072 sc0 sc1
	s_waitcnt vmcnt(0)
	s_barrier
	s_cmp_lg_u32 s49, 0
	s_cbranch_scc1 .Lks_skip_epi
	s_mov_b64 exec, 1
	global_atomic_add v179, v180, s[76:77]
	s_mov_b64 exec, -1
	s_branch .Lks_skip_epi
.Lks_normal:
	ds_read_b32 v182, v170
	ds_read_b32 v183, v170 offset:64
	ds_read_b32 v184, v170 offset:128
	ds_read_b32 v185, v170 offset:192
	ds_read_b32 v186, v170 offset:512
	ds_read_b32 v187, v170 offset:576
	ds_read_b32 v188, v170 offset:640
	ds_read_b32 v189, v170 offset:704
	v_add_u32_e32 v203, s11, v166
	v_lshl_or_b32 v202, s60, 7, v171
	v_lshlrev_b32_e32 v202, 1, v202
	v_mad_u32_u24 v202, v203, s86, v202
	s_waitcnt lgkmcnt(0)
	v_fma_f32 v132, v132, v182, v238
	v_fma_f32 v133, v133, v182, v239
	v_fma_f32 v134, v134, v182, v240
	v_fma_f32 v135, v135, v182, v241
	v_fma_f32 v124, v124, v182, v242
	v_fma_f32 v125, v125, v182, v243
	v_fma_f32 v126, v126, v182, v244
	v_fma_f32 v127, v127, v182, v245
	v_fma_f32 v128, v128, v182, v246
	v_fma_f32 v129, v129, v182, v247
	v_fma_f32 v130, v130, v182, v248
	v_fma_f32 v131, v131, v182, v249
	v_fma_f32 v120, v120, v182, v250
	v_fma_f32 v121, v121, v182, v251
	v_fma_f32 v122, v122, v182, v252
	v_fma_f32 v123, v123, v182, v253
	v_mul_f32_e32 v190, 0xbfb8aa3b, v132
	v_mul_f32_e32 v191, 0xbfb8aa3b, v133
	v_mul_f32_e32 v192, 0xbfb8aa3b, v134
	v_mul_f32_e32 v193, 0xbfb8aa3b, v135
	v_mul_f32_e32 v194, 0xbfb8aa3b, v124
	v_mul_f32_e32 v195, 0xbfb8aa3b, v125
	v_mul_f32_e32 v196, 0xbfb8aa3b, v126
	v_mul_f32_e32 v197, 0xbfb8aa3b, v127
	v_exp_f32_e32 v190, v190
	v_exp_f32_e32 v191, v191
	v_exp_f32_e32 v192, v192
	v_exp_f32_e32 v193, v193
	v_exp_f32_e32 v194, v194
	v_exp_f32_e32 v195, v195
	v_exp_f32_e32 v196, v196
	v_exp_f32_e32 v197, v197
	v_add_f32_e32 v190, 1.0, v190
	v_add_f32_e32 v191, 1.0, v191
	v_add_f32_e32 v192, 1.0, v192
	v_add_f32_e32 v193, 1.0, v193
	v_add_f32_e32 v194, 1.0, v194
	v_add_f32_e32 v195, 1.0, v195
	v_add_f32_e32 v196, 1.0, v196
	v_add_f32_e32 v197, 1.0, v197
	v_rcp_f32_e32 v190, v190
	v_rcp_f32_e32 v191, v191
	v_rcp_f32_e32 v192, v192
	v_rcp_f32_e32 v193, v193
	v_rcp_f32_e32 v194, v194
	v_rcp_f32_e32 v195, v195
	v_rcp_f32_e32 v196, v196
	v_rcp_f32_e32 v197, v197
	v_mul_f32_e32 v132, v132, v190
	v_mul_f32_e32 v133, v133, v191
	v_mul_f32_e32 v134, v134, v192
	v_mul_f32_e32 v135, v135, v193
	v_mul_f32_e32 v124, v124, v194
	v_mul_f32_e32 v125, v125, v195
	v_mul_f32_e32 v126, v126, v196
	v_mul_f32_e32 v127, v127, v197
	v_mul_f32_e32 v132, v132, v128
	v_mul_f32_e32 v133, v133, v129
	v_mul_f32_e32 v134, v134, v130
	v_mul_f32_e32 v135, v135, v131
	v_mul_f32_e32 v124, v124, v120
	v_mul_f32_e32 v125, v125, v121
	v_mul_f32_e32 v126, v126, v122
	v_mul_f32_e32 v127, v127, v123
	v_cvt_pk_bf16_f32 v198, v132, v133
	v_cvt_pk_bf16_f32 v199, v134, v135
	v_cvt_pk_bf16_f32 v200, v124, v125
	v_cvt_pk_bf16_f32 v201, v126, v127
	global_store_dwordx4 v202, v[198:201], s[6:7]
	v_fma_f32 v116, v116, v183, v238
	v_fma_f32 v117, v117, v183, v239
	v_fma_f32 v118, v118, v183, v240
	v_fma_f32 v119, v119, v183, v241
	v_fma_f32 v112, v112, v183, v242
	v_fma_f32 v113, v113, v183, v243
	v_fma_f32 v114, v114, v183, v244
	v_fma_f32 v115, v115, v183, v245
	v_fma_f32 v108, v108, v183, v246
	v_fma_f32 v109, v109, v183, v247
	v_fma_f32 v110, v110, v183, v248
	v_fma_f32 v111, v111, v183, v249
	v_fma_f32 v104, v104, v183, v250
	v_fma_f32 v105, v105, v183, v251
	v_fma_f32 v106, v106, v183, v252
	v_fma_f32 v107, v107, v183, v253
	v_mul_f32_e32 v190, 0xbfb8aa3b, v116
	v_mul_f32_e32 v191, 0xbfb8aa3b, v117
	v_mul_f32_e32 v192, 0xbfb8aa3b, v118
	v_mul_f32_e32 v193, 0xbfb8aa3b, v119
	v_mul_f32_e32 v194, 0xbfb8aa3b, v112
	v_mul_f32_e32 v195, 0xbfb8aa3b, v113
	v_mul_f32_e32 v196, 0xbfb8aa3b, v114
	v_mul_f32_e32 v197, 0xbfb8aa3b, v115
	v_exp_f32_e32 v190, v190
	v_exp_f32_e32 v191, v191
	v_exp_f32_e32 v192, v192
	v_exp_f32_e32 v193, v193
	v_exp_f32_e32 v194, v194
	v_exp_f32_e32 v195, v195
	v_exp_f32_e32 v196, v196
	v_exp_f32_e32 v197, v197
	v_add_f32_e32 v190, 1.0, v190
	v_add_f32_e32 v191, 1.0, v191
	v_add_f32_e32 v192, 1.0, v192
	v_add_f32_e32 v193, 1.0, v193
	v_add_f32_e32 v194, 1.0, v194
	v_add_f32_e32 v195, 1.0, v195
	v_add_f32_e32 v196, 1.0, v196
	v_add_f32_e32 v197, 1.0, v197
	v_rcp_f32_e32 v190, v190
	v_rcp_f32_e32 v191, v191
	v_rcp_f32_e32 v192, v192
	v_rcp_f32_e32 v193, v193
	v_rcp_f32_e32 v194, v194
	v_rcp_f32_e32 v195, v195
	v_rcp_f32_e32 v196, v196
	v_rcp_f32_e32 v197, v197
	v_mul_f32_e32 v116, v116, v190
	v_mul_f32_e32 v117, v117, v191
	v_mul_f32_e32 v118, v118, v192
	v_mul_f32_e32 v119, v119, v193
	v_mul_f32_e32 v112, v112, v194
	v_mul_f32_e32 v113, v113, v195
	v_mul_f32_e32 v114, v114, v196
	v_mul_f32_e32 v115, v115, v197
	v_mul_f32_e32 v116, v116, v108
	v_mul_f32_e32 v117, v117, v109
	v_mul_f32_e32 v118, v118, v110
	v_mul_f32_e32 v119, v119, v111
	v_mul_f32_e32 v112, v112, v104
	v_mul_f32_e32 v113, v113, v105
	v_mul_f32_e32 v114, v114, v106
	v_mul_f32_e32 v115, v115, v107
	v_cvt_pk_bf16_f32 v198, v116, v117
	v_cvt_pk_bf16_f32 v199, v118, v119
	v_cvt_pk_bf16_f32 v200, v112, v113
	v_cvt_pk_bf16_f32 v201, v114, v115
	v_add_u32_e32 v203, 0x16000, v202
	s_nop 0
	global_store_dwordx4 v203, v[198:201], s[6:7]
	v_fma_f32 v100, v100, v184, v238
	v_fma_f32 v101, v101, v184, v239
	v_fma_f32 v102, v102, v184, v240
	v_fma_f32 v103, v103, v184, v241
	v_fma_f32 v96, v96, v184, v242
	v_fma_f32 v97, v97, v184, v243
	v_fma_f32 v98, v98, v184, v244
	v_fma_f32 v99, v99, v184, v245
	v_fma_f32 v92, v92, v184, v246
	v_fma_f32 v93, v93, v184, v247
	v_fma_f32 v94, v94, v184, v248
	v_fma_f32 v95, v95, v184, v249
	v_fma_f32 v88, v88, v184, v250
	v_fma_f32 v89, v89, v184, v251
	v_fma_f32 v90, v90, v184, v252
	v_fma_f32 v91, v91, v184, v253
	v_mul_f32_e32 v190, 0xbfb8aa3b, v100
	v_mul_f32_e32 v191, 0xbfb8aa3b, v101
	v_mul_f32_e32 v192, 0xbfb8aa3b, v102
	v_mul_f32_e32 v193, 0xbfb8aa3b, v103
	v_mul_f32_e32 v194, 0xbfb8aa3b, v96
	v_mul_f32_e32 v195, 0xbfb8aa3b, v97
	v_mul_f32_e32 v196, 0xbfb8aa3b, v98
	v_mul_f32_e32 v197, 0xbfb8aa3b, v99
	v_exp_f32_e32 v190, v190
	v_exp_f32_e32 v191, v191
	v_exp_f32_e32 v192, v192
	v_exp_f32_e32 v193, v193
	v_exp_f32_e32 v194, v194
	v_exp_f32_e32 v195, v195
	v_exp_f32_e32 v196, v196
	v_exp_f32_e32 v197, v197
	v_add_f32_e32 v190, 1.0, v190
	v_add_f32_e32 v191, 1.0, v191
	v_add_f32_e32 v192, 1.0, v192
	v_add_f32_e32 v193, 1.0, v193
	v_add_f32_e32 v194, 1.0, v194
	v_add_f32_e32 v195, 1.0, v195
	v_add_f32_e32 v196, 1.0, v196
	v_add_f32_e32 v197, 1.0, v197
	v_rcp_f32_e32 v190, v190
	v_rcp_f32_e32 v191, v191
	v_rcp_f32_e32 v192, v192
	v_rcp_f32_e32 v193, v193
	v_rcp_f32_e32 v194, v194
	v_rcp_f32_e32 v195, v195
	v_rcp_f32_e32 v196, v196
	v_rcp_f32_e32 v197, v197
	v_mul_f32_e32 v100, v100, v190
	v_mul_f32_e32 v101, v101, v191
	v_mul_f32_e32 v102, v102, v192
	v_mul_f32_e32 v103, v103, v193
	v_mul_f32_e32 v96, v96, v194
	v_mul_f32_e32 v97, v97, v195
	v_mul_f32_e32 v98, v98, v196
	v_mul_f32_e32 v99, v99, v197
	v_mul_f32_e32 v100, v100, v92
	v_mul_f32_e32 v101, v101, v93
	v_mul_f32_e32 v102, v102, v94
	v_mul_f32_e32 v103, v103, v95
	v_mul_f32_e32 v96, v96, v88
	v_mul_f32_e32 v97, v97, v89
	v_mul_f32_e32 v98, v98, v90
	v_mul_f32_e32 v99, v99, v91
	v_cvt_pk_bf16_f32 v198, v100, v101
	v_cvt_pk_bf16_f32 v199, v102, v103
	v_cvt_pk_bf16_f32 v200, v96, v97
	v_cvt_pk_bf16_f32 v201, v98, v99
	v_add_u32_e32 v203, 0x2c000, v202
	s_nop 0
	global_store_dwordx4 v203, v[198:201], s[6:7]
	v_fma_f32 v84, v84, v185, v238
	v_fma_f32 v85, v85, v185, v239
	v_fma_f32 v86, v86, v185, v240
	v_fma_f32 v87, v87, v185, v241
	v_fma_f32 v80, v80, v185, v242
	v_fma_f32 v81, v81, v185, v243
	v_fma_f32 v82, v82, v185, v244
	v_fma_f32 v83, v83, v185, v245
	v_fma_f32 v76, v76, v185, v246
	v_fma_f32 v77, v77, v185, v247
	v_fma_f32 v78, v78, v185, v248
	v_fma_f32 v79, v79, v185, v249
	v_fma_f32 v72, v72, v185, v250
	v_fma_f32 v73, v73, v185, v251
	v_fma_f32 v74, v74, v185, v252
	v_fma_f32 v75, v75, v185, v253
	v_mul_f32_e32 v190, 0xbfb8aa3b, v84
	v_mul_f32_e32 v191, 0xbfb8aa3b, v85
	v_mul_f32_e32 v192, 0xbfb8aa3b, v86
	v_mul_f32_e32 v193, 0xbfb8aa3b, v87
	v_mul_f32_e32 v194, 0xbfb8aa3b, v80
	v_mul_f32_e32 v195, 0xbfb8aa3b, v81
	v_mul_f32_e32 v196, 0xbfb8aa3b, v82
	v_mul_f32_e32 v197, 0xbfb8aa3b, v83
	v_exp_f32_e32 v190, v190
	v_exp_f32_e32 v191, v191
	v_exp_f32_e32 v192, v192
	v_exp_f32_e32 v193, v193
	v_exp_f32_e32 v194, v194
	v_exp_f32_e32 v195, v195
	v_exp_f32_e32 v196, v196
	v_exp_f32_e32 v197, v197
	v_add_f32_e32 v190, 1.0, v190
	v_add_f32_e32 v191, 1.0, v191
	v_add_f32_e32 v192, 1.0, v192
	v_add_f32_e32 v193, 1.0, v193
	v_add_f32_e32 v194, 1.0, v194
	v_add_f32_e32 v195, 1.0, v195
	v_add_f32_e32 v196, 1.0, v196
	v_add_f32_e32 v197, 1.0, v197
	v_rcp_f32_e32 v190, v190
	v_rcp_f32_e32 v191, v191
	v_rcp_f32_e32 v192, v192
	v_rcp_f32_e32 v193, v193
	v_rcp_f32_e32 v194, v194
	v_rcp_f32_e32 v195, v195
	v_rcp_f32_e32 v196, v196
	v_rcp_f32_e32 v197, v197
	v_mul_f32_e32 v84, v84, v190
	v_mul_f32_e32 v85, v85, v191
	v_mul_f32_e32 v86, v86, v192
	v_mul_f32_e32 v87, v87, v193
	v_mul_f32_e32 v80, v80, v194
	v_mul_f32_e32 v81, v81, v195
	v_mul_f32_e32 v82, v82, v196
	v_mul_f32_e32 v83, v83, v197
	v_mul_f32_e32 v84, v84, v76
	v_mul_f32_e32 v85, v85, v77
	v_mul_f32_e32 v86, v86, v78
	v_mul_f32_e32 v87, v87, v79
	v_mul_f32_e32 v80, v80, v72
	v_mul_f32_e32 v81, v81, v73
	v_mul_f32_e32 v82, v82, v74
	v_mul_f32_e32 v83, v83, v75
	v_cvt_pk_bf16_f32 v198, v84, v85
	v_cvt_pk_bf16_f32 v199, v86, v87
	v_cvt_pk_bf16_f32 v200, v80, v81
	v_cvt_pk_bf16_f32 v201, v82, v83
	v_add_u32_e32 v203, 0x42000, v202
	s_nop 0
	global_store_dwordx4 v203, v[198:201], s[6:7]
	v_fma_f32 v68, v68, v186, v238
	v_fma_f32 v69, v69, v186, v239
	v_fma_f32 v70, v70, v186, v240
	v_fma_f32 v71, v71, v186, v241
	v_fma_f32 v64, v64, v186, v242
	v_fma_f32 v65, v65, v186, v243
	v_fma_f32 v66, v66, v186, v244
	v_fma_f32 v67, v67, v186, v245
	v_fma_f32 v60, v60, v186, v246
	v_fma_f32 v61, v61, v186, v247
	v_fma_f32 v62, v62, v186, v248
	v_fma_f32 v63, v63, v186, v249
	v_fma_f32 v52, v52, v186, v250
	v_fma_f32 v53, v53, v186, v251
	v_fma_f32 v54, v54, v186, v252
	v_fma_f32 v55, v55, v186, v253
	v_mul_f32_e32 v190, 0xbfb8aa3b, v68
	v_mul_f32_e32 v191, 0xbfb8aa3b, v69
	v_mul_f32_e32 v192, 0xbfb8aa3b, v70
	v_mul_f32_e32 v193, 0xbfb8aa3b, v71
	v_mul_f32_e32 v194, 0xbfb8aa3b, v64
	v_mul_f32_e32 v195, 0xbfb8aa3b, v65
	v_mul_f32_e32 v196, 0xbfb8aa3b, v66
	v_mul_f32_e32 v197, 0xbfb8aa3b, v67
	v_exp_f32_e32 v190, v190
	v_exp_f32_e32 v191, v191
	v_exp_f32_e32 v192, v192
	v_exp_f32_e32 v193, v193
	v_exp_f32_e32 v194, v194
	v_exp_f32_e32 v195, v195
	v_exp_f32_e32 v196, v196
	v_exp_f32_e32 v197, v197
	v_add_f32_e32 v190, 1.0, v190
	v_add_f32_e32 v191, 1.0, v191
	v_add_f32_e32 v192, 1.0, v192
	v_add_f32_e32 v193, 1.0, v193
	v_add_f32_e32 v194, 1.0, v194
	v_add_f32_e32 v195, 1.0, v195
	v_add_f32_e32 v196, 1.0, v196
	v_add_f32_e32 v197, 1.0, v197
	v_rcp_f32_e32 v190, v190
	v_rcp_f32_e32 v191, v191
	v_rcp_f32_e32 v192, v192
	v_rcp_f32_e32 v193, v193
	v_rcp_f32_e32 v194, v194
	v_rcp_f32_e32 v195, v195
	v_rcp_f32_e32 v196, v196
	v_rcp_f32_e32 v197, v197
	v_mul_f32_e32 v68, v68, v190
	v_mul_f32_e32 v69, v69, v191
	v_mul_f32_e32 v70, v70, v192
	v_mul_f32_e32 v71, v71, v193
	v_mul_f32_e32 v64, v64, v194
	v_mul_f32_e32 v65, v65, v195
	v_mul_f32_e32 v66, v66, v196
	v_mul_f32_e32 v67, v67, v197
	v_mul_f32_e32 v68, v68, v60
	v_mul_f32_e32 v69, v69, v61
	v_mul_f32_e32 v70, v70, v62
	v_mul_f32_e32 v71, v71, v63
	v_mul_f32_e32 v64, v64, v52
	v_mul_f32_e32 v65, v65, v53
	v_mul_f32_e32 v66, v66, v54
	v_mul_f32_e32 v67, v67, v55
	v_cvt_pk_bf16_f32 v198, v68, v69
	v_cvt_pk_bf16_f32 v199, v70, v71
	v_cvt_pk_bf16_f32 v200, v64, v65
	v_cvt_pk_bf16_f32 v201, v66, v67
	v_add_u32_e32 v203, 0xb0000, v202
	s_nop 0
	global_store_dwordx4 v203, v[198:201], s[6:7]
	v_fma_f32 v44, v44, v187, v238
	v_fma_f32 v45, v45, v187, v239
	v_fma_f32 v46, v46, v187, v240
	v_fma_f32 v47, v47, v187, v241
	v_fma_f32 v40, v40, v187, v242
	v_fma_f32 v41, v41, v187, v243
	v_fma_f32 v42, v42, v187, v244
	v_fma_f32 v43, v43, v187, v245
	v_fma_f32 v36, v36, v187, v246
	v_fma_f32 v37, v37, v187, v247
	v_fma_f32 v38, v38, v187, v248
	v_fma_f32 v39, v39, v187, v249
	v_fma_f32 v32, v32, v187, v250
	v_fma_f32 v33, v33, v187, v251
	v_fma_f32 v34, v34, v187, v252
	v_fma_f32 v35, v35, v187, v253
	v_mul_f32_e32 v190, 0xbfb8aa3b, v44
	v_mul_f32_e32 v191, 0xbfb8aa3b, v45
	v_mul_f32_e32 v192, 0xbfb8aa3b, v46
	v_mul_f32_e32 v193, 0xbfb8aa3b, v47
	v_mul_f32_e32 v194, 0xbfb8aa3b, v40
	v_mul_f32_e32 v195, 0xbfb8aa3b, v41
	v_mul_f32_e32 v196, 0xbfb8aa3b, v42
	v_mul_f32_e32 v197, 0xbfb8aa3b, v43
	v_exp_f32_e32 v190, v190
	v_exp_f32_e32 v191, v191
	v_exp_f32_e32 v192, v192
	v_exp_f32_e32 v193, v193
	v_exp_f32_e32 v194, v194
	v_exp_f32_e32 v195, v195
	v_exp_f32_e32 v196, v196
	v_exp_f32_e32 v197, v197
	v_add_f32_e32 v190, 1.0, v190
	v_add_f32_e32 v191, 1.0, v191
	v_add_f32_e32 v192, 1.0, v192
	v_add_f32_e32 v193, 1.0, v193
	v_add_f32_e32 v194, 1.0, v194
	v_add_f32_e32 v195, 1.0, v195
	v_add_f32_e32 v196, 1.0, v196
	v_add_f32_e32 v197, 1.0, v197
	v_rcp_f32_e32 v190, v190
	v_rcp_f32_e32 v191, v191
	v_rcp_f32_e32 v192, v192
	v_rcp_f32_e32 v193, v193
	v_rcp_f32_e32 v194, v194
	v_rcp_f32_e32 v195, v195
	v_rcp_f32_e32 v196, v196
	v_rcp_f32_e32 v197, v197
	v_mul_f32_e32 v44, v44, v190
	v_mul_f32_e32 v45, v45, v191
	v_mul_f32_e32 v46, v46, v192
	v_mul_f32_e32 v47, v47, v193
	v_mul_f32_e32 v40, v40, v194
	v_mul_f32_e32 v41, v41, v195
	v_mul_f32_e32 v42, v42, v196
	v_mul_f32_e32 v43, v43, v197
	v_mul_f32_e32 v44, v44, v36
	v_mul_f32_e32 v45, v45, v37
	v_mul_f32_e32 v46, v46, v38
	v_mul_f32_e32 v47, v47, v39
	v_mul_f32_e32 v40, v40, v32
	v_mul_f32_e32 v41, v41, v33
	v_mul_f32_e32 v42, v42, v34
	v_mul_f32_e32 v43, v43, v35
	v_cvt_pk_bf16_f32 v198, v44, v45
	v_cvt_pk_bf16_f32 v199, v46, v47
	v_cvt_pk_bf16_f32 v200, v40, v41
	v_cvt_pk_bf16_f32 v201, v42, v43
	v_add_u32_e32 v203, 0xc6000, v202
	s_nop 0
	global_store_dwordx4 v203, v[198:201], s[6:7]
	v_fma_f32 v28, v28, v188, v238
	v_fma_f32 v29, v29, v188, v239
	v_fma_f32 v30, v30, v188, v240
	v_fma_f32 v31, v31, v188, v241
	v_fma_f32 v24, v24, v188, v242
	v_fma_f32 v25, v25, v188, v243
	v_fma_f32 v26, v26, v188, v244
	v_fma_f32 v27, v27, v188, v245
	v_fma_f32 v20, v20, v188, v246
	v_fma_f32 v21, v21, v188, v247
	v_fma_f32 v22, v22, v188, v248
	v_fma_f32 v23, v23, v188, v249
	v_fma_f32 v16, v16, v188, v250
	v_fma_f32 v17, v17, v188, v251
	v_fma_f32 v18, v18, v188, v252
	v_fma_f32 v19, v19, v188, v253
	v_mul_f32_e32 v190, 0xbfb8aa3b, v28
	v_mul_f32_e32 v191, 0xbfb8aa3b, v29
	v_mul_f32_e32 v192, 0xbfb8aa3b, v30
	v_mul_f32_e32 v193, 0xbfb8aa3b, v31
	v_mul_f32_e32 v194, 0xbfb8aa3b, v24
	v_mul_f32_e32 v195, 0xbfb8aa3b, v25
	v_mul_f32_e32 v196, 0xbfb8aa3b, v26
	v_mul_f32_e32 v197, 0xbfb8aa3b, v27
	v_exp_f32_e32 v190, v190
	v_exp_f32_e32 v191, v191
	v_exp_f32_e32 v192, v192
	v_exp_f32_e32 v193, v193
	v_exp_f32_e32 v194, v194
	v_exp_f32_e32 v195, v195
	v_exp_f32_e32 v196, v196
	v_exp_f32_e32 v197, v197
	v_add_f32_e32 v190, 1.0, v190
	v_add_f32_e32 v191, 1.0, v191
	v_add_f32_e32 v192, 1.0, v192
	v_add_f32_e32 v193, 1.0, v193
	v_add_f32_e32 v194, 1.0, v194
	v_add_f32_e32 v195, 1.0, v195
	v_add_f32_e32 v196, 1.0, v196
	v_add_f32_e32 v197, 1.0, v197
	v_rcp_f32_e32 v190, v190
	v_rcp_f32_e32 v191, v191
	v_rcp_f32_e32 v192, v192
	v_rcp_f32_e32 v193, v193
	v_rcp_f32_e32 v194, v194
	v_rcp_f32_e32 v195, v195
	v_rcp_f32_e32 v196, v196
	v_rcp_f32_e32 v197, v197
	v_mul_f32_e32 v28, v28, v190
	v_mul_f32_e32 v29, v29, v191
	v_mul_f32_e32 v30, v30, v192
	v_mul_f32_e32 v31, v31, v193
	v_mul_f32_e32 v24, v24, v194
	v_mul_f32_e32 v25, v25, v195
	v_mul_f32_e32 v26, v26, v196
	v_mul_f32_e32 v27, v27, v197
	v_mul_f32_e32 v28, v28, v20
	v_mul_f32_e32 v29, v29, v21
	v_mul_f32_e32 v30, v30, v22
	v_mul_f32_e32 v31, v31, v23
	v_mul_f32_e32 v24, v24, v16
	v_mul_f32_e32 v25, v25, v17
	v_mul_f32_e32 v26, v26, v18
	v_mul_f32_e32 v27, v27, v19
	v_cvt_pk_bf16_f32 v198, v28, v29
	v_cvt_pk_bf16_f32 v199, v30, v31
	v_cvt_pk_bf16_f32 v200, v24, v25
	v_cvt_pk_bf16_f32 v201, v26, v27
	v_add_u32_e32 v203, 0xdc000, v202
	s_nop 0
	global_store_dwordx4 v203, v[198:201], s[6:7]
	v_fma_f32 v12, v12, v189, v238
	v_fma_f32 v13, v13, v189, v239
	v_fma_f32 v14, v14, v189, v240
	v_fma_f32 v15, v15, v189, v241
	v_fma_f32 v8, v8, v189, v242
	v_fma_f32 v9, v9, v189, v243
	v_fma_f32 v10, v10, v189, v244
	v_fma_f32 v11, v11, v189, v245
	v_fma_f32 v4, v4, v189, v246
	v_fma_f32 v5, v5, v189, v247
	v_fma_f32 v6, v6, v189, v248
	v_fma_f32 v7, v7, v189, v249
	v_fma_f32 v0, v0, v189, v250
	v_fma_f32 v1, v1, v189, v251
	v_fma_f32 v2, v2, v189, v252
	v_fma_f32 v3, v3, v189, v253
	v_mul_f32_e32 v190, 0xbfb8aa3b, v12
	v_mul_f32_e32 v191, 0xbfb8aa3b, v13
	v_mul_f32_e32 v192, 0xbfb8aa3b, v14
	v_mul_f32_e32 v193, 0xbfb8aa3b, v15
	v_mul_f32_e32 v194, 0xbfb8aa3b, v8
	v_mul_f32_e32 v195, 0xbfb8aa3b, v9
	v_mul_f32_e32 v196, 0xbfb8aa3b, v10
	v_mul_f32_e32 v197, 0xbfb8aa3b, v11
	v_exp_f32_e32 v190, v190
	v_exp_f32_e32 v191, v191
	v_exp_f32_e32 v192, v192
	v_exp_f32_e32 v193, v193
	v_exp_f32_e32 v194, v194
	v_exp_f32_e32 v195, v195
	v_exp_f32_e32 v196, v196
	v_exp_f32_e32 v197, v197
	v_add_f32_e32 v190, 1.0, v190
	v_add_f32_e32 v191, 1.0, v191
	v_add_f32_e32 v192, 1.0, v192
	v_add_f32_e32 v193, 1.0, v193
	v_add_f32_e32 v194, 1.0, v194
	v_add_f32_e32 v195, 1.0, v195
	v_add_f32_e32 v196, 1.0, v196
	v_add_f32_e32 v197, 1.0, v197
	v_rcp_f32_e32 v190, v190
	v_rcp_f32_e32 v191, v191
	v_rcp_f32_e32 v192, v192
	v_rcp_f32_e32 v193, v193
	v_rcp_f32_e32 v194, v194
	v_rcp_f32_e32 v195, v195
	v_rcp_f32_e32 v196, v196
	v_rcp_f32_e32 v197, v197
	v_mul_f32_e32 v12, v12, v190
	v_mul_f32_e32 v13, v13, v191
	v_mul_f32_e32 v14, v14, v192
	v_mul_f32_e32 v15, v15, v193
	v_mul_f32_e32 v8, v8, v194
	v_mul_f32_e32 v9, v9, v195
	v_mul_f32_e32 v10, v10, v196
	v_mul_f32_e32 v11, v11, v197
	v_mul_f32_e32 v12, v12, v4
	v_mul_f32_e32 v13, v13, v5
	v_mul_f32_e32 v14, v14, v6
	v_mul_f32_e32 v15, v15, v7
	v_mul_f32_e32 v8, v8, v0
	v_mul_f32_e32 v9, v9, v1
	v_mul_f32_e32 v10, v10, v2
	v_mul_f32_e32 v11, v11, v3
	v_cvt_pk_bf16_f32 v198, v12, v13
	v_cvt_pk_bf16_f32 v199, v14, v15
	v_cvt_pk_bf16_f32 v200, v8, v9
	v_cvt_pk_bf16_f32 v201, v10, v11
	v_add_u32_e32 v203, 0xf2000, v202
	s_nop 0
	global_store_dwordx4 v203, v[198:201], s[6:7]
.Lks_skip_epi:
	s_andn2_b64 vcc, exec, s[4:5]
	s_cbranch_vccnz .LBB0_248
	s_andn2_b64 vcc, exec, s[0:1]
	s_cbranch_vccnz .LBB0_247
	s_barrier
	s_branch .LBB0_247
